# attention unit 1: QK and PV MFMA blocks regenerated with a 6-deep LDS fragment prefetch ring in free registers; first PV reads issued behind QK
# baseline (speedup 1.0000x reference)
.LBB0_1483:
	s_bitcmp1_b32 s51, 0
	s_cselect_b32 s53, 0, 0xac00
	s_setprio 1
	v_add_u32_e32 v253, s53, v171
	v_add_u32_e32 v252, s53, v181
	ds_read_b128 v[196:199], v253
	ds_read_b128 v[200:203], v253 offset:12800
	ds_read_b128 v[204:207], v253 offset:32
	ds_read_b128 v[208:211], v253 offset:12832
	ds_read_b128 v[212:215], v253 offset:64
	ds_read_b128 v[216:219], v253 offset:12864
	s_waitcnt lgkmcnt(5)
	v_mfma_f32_32x32x16_bf16 v[66:81], v[196:199], v[110:113], 0
	ds_read_b128 v[220:223], v253 offset:96
	s_waitcnt lgkmcnt(5)
	v_mfma_f32_32x32x16_bf16 v[82:97], v[200:203], v[110:113], 0
	ds_read_b128 v[196:199], v253 offset:12896
	s_waitcnt lgkmcnt(5)
	v_mfma_f32_32x32x16_bf16 v[66:81], v[204:207], v[118:121], v[66:81]
	ds_read_b128 v[200:203], v253 offset:128
	s_waitcnt lgkmcnt(5)
	v_mfma_f32_32x32x16_bf16 v[82:97], v[208:211], v[118:121], v[82:97]
	ds_read_b128 v[204:207], v253 offset:12928
	s_waitcnt lgkmcnt(5)
	v_mfma_f32_32x32x16_bf16 v[66:81], v[212:215], v[122:125], v[66:81]
	ds_read_b128 v[208:211], v253 offset:160
	s_waitcnt lgkmcnt(5)
	v_mfma_f32_32x32x16_bf16 v[82:97], v[216:219], v[122:125], v[82:97]
	ds_read_b128 v[212:215], v253 offset:12960
	s_waitcnt lgkmcnt(5)
	v_mfma_f32_32x32x16_bf16 v[66:81], v[220:223], v[126:129], v[66:81]
	ds_read_b128 v[216:219], v253 offset:192
	s_waitcnt lgkmcnt(5)
	v_mfma_f32_32x32x16_bf16 v[82:97], v[196:199], v[126:129], v[82:97]
	ds_read_b128 v[220:223], v253 offset:12992
	s_waitcnt lgkmcnt(5)
	v_mfma_f32_32x32x16_bf16 v[66:81], v[200:203], v[130:133], v[66:81]
	ds_read_b128 v[196:199], v253 offset:224
	s_waitcnt lgkmcnt(5)
	v_mfma_f32_32x32x16_bf16 v[82:97], v[204:207], v[130:133], v[82:97]
	ds_read_b128 v[200:203], v253 offset:13024
	s_waitcnt lgkmcnt(5)
	v_mfma_f32_32x32x16_bf16 v[66:81], v[208:211], v[134:137], v[66:81]
	ds_read_b128 v[204:207], v253 offset:256
	s_waitcnt lgkmcnt(5)
	v_mfma_f32_32x32x16_bf16 v[82:97], v[212:215], v[134:137], v[82:97]
	ds_read_b128 v[208:211], v253 offset:13056
	s_waitcnt lgkmcnt(5)
	v_mfma_f32_32x32x16_bf16 v[66:81], v[216:219], v[138:141], v[66:81]
	ds_read_b128 v[212:215], v253 offset:288
	s_waitcnt lgkmcnt(5)
	v_mfma_f32_32x32x16_bf16 v[82:97], v[220:223], v[138:141], v[82:97]
	ds_read_b128 v[216:219], v253 offset:13088
	s_waitcnt lgkmcnt(5)
	v_mfma_f32_32x32x16_bf16 v[66:81], v[196:199], v[142:145], v[66:81]
	ds_read_b128 v[220:223], v253 offset:320
	s_waitcnt lgkmcnt(5)
	v_mfma_f32_32x32x16_bf16 v[82:97], v[200:203], v[142:145], v[82:97]
	ds_read_b128 v[196:199], v253 offset:13120
	s_waitcnt lgkmcnt(5)
	v_mfma_f32_32x32x16_bf16 v[66:81], v[204:207], v[150:153], v[66:81]
	ds_read_b128 v[200:203], v253 offset:352
	s_waitcnt lgkmcnt(5)
	v_mfma_f32_32x32x16_bf16 v[82:97], v[208:211], v[150:153], v[82:97]
	ds_read_b128 v[204:207], v253 offset:13152
	s_waitcnt lgkmcnt(5)
	v_mfma_f32_32x32x16_bf16 v[66:81], v[212:215], v[154:157], v[66:81]
	s_waitcnt lgkmcnt(4)
	v_mfma_f32_32x32x16_bf16 v[82:97], v[216:219], v[154:157], v[82:97]
	s_waitcnt lgkmcnt(3)
	v_mfma_f32_32x32x16_bf16 v[66:81], v[220:223], v[158:161], v[66:81]
	s_waitcnt lgkmcnt(2)
	v_mfma_f32_32x32x16_bf16 v[82:97], v[196:199], v[158:161], v[82:97]
	s_waitcnt lgkmcnt(1)
	v_mfma_f32_32x32x16_bf16 v[66:81], v[200:203], v[162:165], v[66:81]
	s_waitcnt lgkmcnt(0)
	v_mfma_f32_32x32x16_bf16 v[82:97], v[204:207], v[162:165], v[82:97]
	ds_read_b128 v[224:227], v252 offset:25600
	ds_read_b128 v[228:231], v252 offset:25632
	ds_read_b128 v[232:235], v252 offset:25664
	ds_read_b128 v[236:239], v252 offset:25696
	ds_read_b128 v[240:243], v252 offset:30208
	ds_read_b128 v[244:247], v252 offset:30240
	s_setprio 0
	s_add_i32 s54, s52, 63
	s_cmp_le_i32 s54, s47
	s_cbranch_scc1 .LBB0_1485
	v_add_u32_e32 v0, s52, v168
	v_add_u32_e32 v184, 32, v0
	v_cmp_le_i32_e32 vcc, v184, v173
	v_add_u32_e32 v184, 33, v0
	s_nop 3
	v_cndmask_b32_e32 v82, v180, v82, vcc
	v_cmp_lt_i32_e32 vcc, v0, v173
	s_nop 1
	v_cndmask_b32_e32 v67, v180, v67, vcc
	v_cmp_le_i32_e32 vcc, v0, v173
	s_nop 1
	v_cndmask_b32_e32 v66, v180, v66, vcc
	v_cmp_le_i32_e32 vcc, v184, v173
	v_add_u32_e32 v184, 2, v0
	s_nop 0
	v_cndmask_b32_e32 v83, v180, v83, vcc
	v_cmp_le_i32_e32 vcc, v184, v173
	v_add_u32_e32 v184, 34, v0
	s_nop 0
	v_cndmask_b32_e32 v68, v180, v68, vcc
	v_cmp_le_i32_e32 vcc, v184, v173
	v_add_u32_e32 v184, 3, v0
	s_nop 0
	v_cndmask_b32_e32 v84, v180, v84, vcc
	v_cmp_le_i32_e32 vcc, v184, v173
	v_add_u32_e32 v184, 35, v0
	s_nop 0
	v_cndmask_b32_e32 v69, v180, v69, vcc
	v_cmp_le_i32_e32 vcc, v184, v173
	v_add_u32_e32 v184, 4, v0
	s_nop 0
	v_cndmask_b32_e32 v85, v180, v85, vcc
	v_cmp_le_i32_e32 vcc, v184, v173
	v_add_u32_e32 v184, 36, v0
	s_nop 0
	v_cndmask_b32_e32 v70, v180, v70, vcc
	v_cmp_le_i32_e32 vcc, v184, v173
	v_add_u32_e32 v184, 5, v0
	s_nop 0
	v_cndmask_b32_e32 v86, v180, v86, vcc
	v_cmp_le_i32_e32 vcc, v184, v173
	v_add_u32_e32 v184, 37, v0
	s_nop 0
	v_cndmask_b32_e32 v71, v180, v71, vcc
	v_cmp_le_i32_e32 vcc, v184, v173
	v_add_u32_e32 v184, 6, v0
	s_nop 0
	v_cndmask_b32_e32 v87, v180, v87, vcc
	v_cmp_le_i32_e32 vcc, v184, v173
	v_add_u32_e32 v184, 38, v0
	s_nop 0
	v_cndmask_b32_e32 v72, v180, v72, vcc
	v_cmp_le_i32_e32 vcc, v184, v173
	v_add_u32_e32 v184, 7, v0
	s_nop 0
	v_cndmask_b32_e32 v88, v180, v88, vcc
	v_cmp_le_i32_e32 vcc, v184, v173
	v_add_u32_e32 v184, 39, v0
	s_nop 0
	v_cndmask_b32_e32 v73, v180, v73, vcc
	v_cmp_le_i32_e32 vcc, v184, v173
	v_add_u32_e32 v184, 16, v0
	s_nop 0
	v_cndmask_b32_e32 v89, v180, v89, vcc
	v_cmp_le_i32_e32 vcc, v184, v173
	v_add_u32_e32 v184, 48, v0
	s_nop 0
	v_cndmask_b32_e32 v74, v180, v74, vcc
	v_cmp_le_i32_e32 vcc, v184, v173
	v_add_u32_e32 v184, 17, v0
	s_nop 0
	v_cndmask_b32_e32 v90, v180, v90, vcc
	v_cmp_le_i32_e32 vcc, v184, v173
	v_add_u32_e32 v184, 49, v0
	s_nop 0
	v_cndmask_b32_e32 v75, v180, v75, vcc
	v_cmp_le_i32_e32 vcc, v184, v173
	v_add_u32_e32 v184, 18, v0
	s_nop 0
	v_cndmask_b32_e32 v91, v180, v91, vcc
	v_cmp_le_i32_e32 vcc, v184, v173
	v_add_u32_e32 v184, 50, v0
	s_nop 0
	v_cndmask_b32_e32 v76, v180, v76, vcc
	v_cmp_le_i32_e32 vcc, v184, v173
	v_add_u32_e32 v184, 19, v0
	s_nop 0
	v_cndmask_b32_e32 v92, v180, v92, vcc
	v_cmp_le_i32_e32 vcc, v184, v173
	v_add_u32_e32 v184, 51, v0
	s_nop 0
	v_cndmask_b32_e32 v77, v180, v77, vcc
	v_cmp_le_i32_e32 vcc, v184, v173
	v_add_u32_e32 v184, 20, v0
	s_nop 0
	v_cndmask_b32_e32 v93, v180, v93, vcc
	v_cmp_le_i32_e32 vcc, v184, v173
	v_add_u32_e32 v184, 52, v0
	s_nop 0
	v_cndmask_b32_e32 v78, v180, v78, vcc
	v_cmp_le_i32_e32 vcc, v184, v173
	v_add_u32_e32 v184, 21, v0
	s_nop 0
	v_cndmask_b32_e32 v94, v180, v94, vcc
	v_cmp_le_i32_e32 vcc, v184, v173
	v_add_u32_e32 v184, 53, v0
	s_nop 0
	v_cndmask_b32_e32 v79, v180, v79, vcc
	v_cmp_le_i32_e32 vcc, v184, v173
	v_add_u32_e32 v184, 22, v0
	s_nop 0
	v_cndmask_b32_e32 v95, v180, v95, vcc
	v_cmp_le_i32_e32 vcc, v184, v173
	v_add_u32_e32 v184, 54, v0
	s_nop 0
	v_cndmask_b32_e32 v80, v180, v80, vcc
	v_cmp_le_i32_e32 vcc, v184, v173
	v_add_u32_e32 v184, 23, v0
	v_add_u32_e32 v0, 55, v0
	v_cndmask_b32_e32 v96, v180, v96, vcc
	v_cmp_le_i32_e32 vcc, v184, v173
	s_nop 1
	v_cndmask_b32_e32 v81, v180, v81, vcc
	v_cmp_le_i32_e32 vcc, v0, v173
	s_nop 1
	v_cndmask_b32_e32 v97, v180, v97, vcc

.LBB0_1487:
	v_sub_f32_e32 v0, v66, v183
	v_exp_f32_e32 v184, v0
	v_sub_f32_e32 v0, v82, v183
	v_exp_f32_e32 v185, v0
	v_sub_f32_e32 v0, v67, v183
	v_exp_f32_e32 v66, v0
	v_sub_f32_e32 v0, v83, v183
	v_exp_f32_e32 v0, v0
	v_add_f32_e32 v67, v184, v185
	v_pk_add_f32 v[82:83], v[66:67], v[0:1]
	v_sub_f32_e32 v67, v68, v183
	v_sub_f32_e32 v68, v84, v183
	v_pk_add_f32 v[82:83], v[82:83], v[82:83] op_sel_hi:[0,1]
	v_exp_f32_e32 v67, v67
	v_exp_f32_e32 v186, v68
	v_sub_f32_e32 v68, v69, v183
	v_sub_f32_e32 v69, v85, v183
	v_exp_f32_e32 v68, v68
	v_exp_f32_e32 v82, v69
	v_add_f32_e32 v69, v67, v186
	v_cvt_pk_bf16_f32 v66, v184, v66
	v_cvt_pk_bf16_f32 v67, v67, v68
	v_pk_add_f32 v[84:85], v[68:69], v[82:83]
	v_sub_f32_e32 v69, v70, v183
	v_sub_f32_e32 v70, v86, v183
	v_pk_add_f32 v[84:85], v[84:85], v[84:85] op_sel_hi:[0,1]
	v_exp_f32_e32 v69, v69
	v_exp_f32_e32 v83, v70
	v_sub_f32_e32 v70, v71, v183
	v_sub_f32_e32 v71, v87, v183
	v_exp_f32_e32 v70, v70
	v_exp_f32_e32 v84, v71
	v_add_f32_e32 v71, v69, v83
	v_cvt_pk_bf16_f32 v68, v69, v70
	v_pk_add_f32 v[86:87], v[70:71], v[84:85]
	v_sub_f32_e32 v71, v72, v183
	v_sub_f32_e32 v72, v88, v183
	v_pk_add_f32 v[86:87], v[86:87], v[86:87] op_sel_hi:[0,1]
	v_exp_f32_e32 v71, v71
	v_exp_f32_e32 v85, v72
	v_sub_f32_e32 v72, v73, v183
	v_sub_f32_e32 v73, v89, v183
	v_exp_f32_e32 v72, v72
	v_exp_f32_e32 v86, v73
	v_add_f32_e32 v73, v71, v85
	v_cvt_pk_bf16_f32 v69, v71, v72
	v_pk_add_f32 v[88:89], v[72:73], v[86:87]
	v_sub_f32_e32 v73, v74, v183
	v_sub_f32_e32 v74, v90, v183
	v_pk_add_f32 v[88:89], v[88:89], v[88:89] op_sel_hi:[0,1]
	v_exp_f32_e32 v73, v73
	v_exp_f32_e32 v87, v74
	v_sub_f32_e32 v74, v75, v183
	v_sub_f32_e32 v75, v91, v183
	v_exp_f32_e32 v74, v74
	v_exp_f32_e32 v88, v75
	v_add_f32_e32 v75, v73, v87
	v_cvt_pk_bf16_f32 v70, v73, v74
	v_pk_add_f32 v[90:91], v[74:75], v[88:89]
	v_sub_f32_e32 v75, v76, v183
	v_sub_f32_e32 v76, v92, v183
	v_pk_add_f32 v[90:91], v[90:91], v[90:91] op_sel_hi:[0,1]
	v_exp_f32_e32 v75, v75
	v_exp_f32_e32 v89, v76
	v_sub_f32_e32 v76, v77, v183
	v_sub_f32_e32 v77, v93, v183
	v_exp_f32_e32 v76, v76
	v_exp_f32_e32 v90, v77
	v_add_f32_e32 v77, v75, v89
	v_cvt_pk_bf16_f32 v71, v75, v76
	v_pk_add_f32 v[92:93], v[76:77], v[90:91]
	v_sub_f32_e32 v77, v78, v183
	v_sub_f32_e32 v78, v94, v183
	v_pk_add_f32 v[92:93], v[92:93], v[92:93] op_sel_hi:[0,1]
	v_exp_f32_e32 v77, v77
	v_exp_f32_e32 v91, v78
	v_sub_f32_e32 v78, v79, v183
	v_sub_f32_e32 v79, v95, v183
	v_exp_f32_e32 v78, v78
	v_exp_f32_e32 v92, v79
	v_add_f32_e32 v79, v77, v91
	v_cvt_pk_bf16_f32 v72, v77, v78
	v_pk_add_f32 v[94:95], v[78:79], v[92:93]
	v_sub_f32_e32 v79, v80, v183
	v_sub_f32_e32 v80, v96, v183
	v_pk_add_f32 v[94:95], v[94:95], v[94:95] op_sel_hi:[0,1]
	v_exp_f32_e32 v79, v79
	v_exp_f32_e32 v93, v80
	v_sub_f32_e32 v80, v81, v183
	v_sub_f32_e32 v81, v97, v183
	v_exp_f32_e32 v80, v80
	v_exp_f32_e32 v94, v81
	v_add_f32_e32 v81, v79, v93
	v_cvt_pk_bf16_f32 v73, v79, v80
	v_cvt_pk_bf16_f32 v74, v185, v0
	v_pk_add_f32 v[96:97], v[80:81], v[94:95]
	v_cvt_pk_bf16_f32 v75, v186, v82
	v_cvt_pk_bf16_f32 v76, v83, v84
	v_cvt_pk_bf16_f32 v77, v85, v86
	v_cvt_pk_bf16_f32 v78, v87, v88
	v_cvt_pk_bf16_f32 v79, v89, v90
	s_nop 0
	v_add_f32_e32 v95, v96, v97
	v_cvt_pk_bf16_f32 v80, v91, v92
	v_cvt_pk_bf16_f32 v81, v93, v94
	s_setprio 1
	v_add_f32_e32 v182, v182, v95
	s_waitcnt lgkmcnt(5)
	v_mfma_f32_32x32x16_bf16 v[50:65], v[224:227], v[66:69], v[50:65]
	ds_read_b128 v[248:251], v252 offset:30272
	s_waitcnt lgkmcnt(5)
	v_mfma_f32_32x32x16_bf16 v[50:65], v[228:231], v[70:73], v[50:65]
	ds_read_b128 v[224:227], v252 offset:30304
	s_waitcnt lgkmcnt(5)
	v_mfma_f32_32x32x16_bf16 v[50:65], v[232:235], v[74:77], v[50:65]
	ds_read_b128 v[228:231], v252 offset:34816
	s_waitcnt lgkmcnt(5)
	v_mfma_f32_32x32x16_bf16 v[50:65], v[236:239], v[78:81], v[50:65]
	ds_read_b128 v[232:235], v252 offset:34848
	s_waitcnt lgkmcnt(5)
	v_mfma_f32_32x32x16_bf16 v[34:49], v[240:243], v[66:69], v[34:49]
	ds_read_b128 v[236:239], v252 offset:34880
	s_waitcnt lgkmcnt(5)
	v_mfma_f32_32x32x16_bf16 v[34:49], v[244:247], v[70:73], v[34:49]
	ds_read_b128 v[240:243], v252 offset:34912
	s_waitcnt lgkmcnt(5)
	v_mfma_f32_32x32x16_bf16 v[34:49], v[248:251], v[74:77], v[34:49]
	ds_read_b128 v[244:247], v252 offset:39424
	s_waitcnt lgkmcnt(5)
	v_mfma_f32_32x32x16_bf16 v[34:49], v[224:227], v[78:81], v[34:49]
	ds_read_b128 v[248:251], v252 offset:39456
	s_waitcnt lgkmcnt(5)
	v_mfma_f32_32x32x16_bf16 v[18:33], v[228:231], v[66:69], v[18:33]
	ds_read_b128 v[224:227], v252 offset:39488
	s_waitcnt lgkmcnt(5)
	v_mfma_f32_32x32x16_bf16 v[18:33], v[232:235], v[70:73], v[18:33]
	ds_read_b128 v[228:231], v252 offset:39520
	s_waitcnt lgkmcnt(5)
	v_mfma_f32_32x32x16_bf16 v[18:33], v[236:239], v[74:77], v[18:33]
	s_waitcnt lgkmcnt(4)
	v_mfma_f32_32x32x16_bf16 v[18:33], v[240:243], v[78:81], v[18:33]
	s_waitcnt lgkmcnt(3)
	v_mfma_f32_32x32x16_bf16 v[2:17], v[244:247], v[66:69], v[2:17]
	s_waitcnt lgkmcnt(2)
	v_mfma_f32_32x32x16_bf16 v[2:17], v[248:251], v[70:73], v[2:17]
	s_waitcnt lgkmcnt(1)
	v_mfma_f32_32x32x16_bf16 v[2:17], v[224:227], v[74:77], v[2:17]
	s_waitcnt lgkmcnt(0)
	v_mfma_f32_32x32x16_bf16 v[2:17], v[228:231], v[78:81], v[2:17]
	s_setprio 0
	s_andn2_b64 vcc, exec, s[36:37]
	s_cbranch_vccnz .LBB0_1478
